# deferral of W_in round 8 into phase 5 plus pipelined first-barrier census loads
# speedup vs baseline: 1.0008x; 1.0008x over previous
.LBB0_510:
	v_readlane_b32 s2, v252, 15
	v_readlane_b32 s3, v252, 16
	v_readlane_b32 s20, v253, 47
	s_nop 3
	global_load_dword v0, v1, s[2:3] sc1
	v_readlane_b32 s2, v252, 17
	v_readlane_b32 s3, v252, 18
	s_waitcnt lgkmcnt(0)
	s_nop 3
	global_load_dword v2, v1, s[2:3] sc1
	v_readlane_b32 s2, v252, 19
	v_readlane_b32 s3, v252, 20
	s_nop 4
	global_load_dword v3, v1, s[2:3] sc1
	v_readlane_b32 s2, v252, 21
	v_readlane_b32 s3, v252, 22
	s_nop 4
	global_load_dword v4, v1, s[2:3] sc1
	v_readlane_b32 s2, v252, 23
	v_readlane_b32 s3, v252, 24
	s_nop 4
	global_load_dword v5, v1, s[2:3] sc1
	v_readlane_b32 s2, v252, 25
	v_readlane_b32 s3, v252, 26
	s_nop 4
	global_load_dword v6, v1, s[2:3] sc1
	v_readlane_b32 s2, v252, 27
	v_readlane_b32 s3, v252, 28
	s_nop 4
	global_load_dword v7, v1, s[2:3] sc1
	v_readlane_b32 s2, v252, 29
	v_readlane_b32 s3, v252, 30
	s_nop 4
	global_load_dword v8, v1, s[2:3] sc1
	v_readlane_b32 s2, v252, 31
	v_readlane_b32 s3, v252, 32
	s_nop 4
	global_load_dword v9, v1, s[2:3] sc1
	v_readlane_b32 s2, v252, 33
	v_readlane_b32 s3, v252, 34
	s_nop 4
	global_load_dword v10, v1, s[2:3] sc1
	v_readlane_b32 s2, v252, 35
	v_readlane_b32 s3, v252, 36
	s_nop 4
	global_load_dword v11, v1, s[2:3] sc1
	v_readlane_b32 s2, v252, 37
	v_readlane_b32 s3, v252, 38
	s_nop 4
	global_load_dword v12, v1, s[2:3] sc1
	v_readlane_b32 s2, v252, 39
	v_readlane_b32 s3, v252, 40
	s_nop 4
	global_load_dword v13, v1, s[2:3] sc1
	v_readlane_b32 s2, v252, 41
	v_readlane_b32 s3, v252, 42
	s_nop 4
	global_load_dword v14, v1, s[2:3] sc1
	v_readlane_b32 s2, v252, 43
	v_readlane_b32 s3, v252, 44
	s_nop 4
	global_load_dword v15, v1, s[2:3] sc1
	v_readlane_b32 s2, v252, 45
	v_readlane_b32 s3, v252, 46
	s_nop 4
	global_load_dword v16, v1, s[2:3] sc1
	s_mov_b64 s[2:3], -1
	s_waitcnt vmcnt(0)
	v_add_u32_e32 v17, v2, v0
	v_add_u32_e32 v17, v17, v3
	v_add_u32_e32 v17, v17, v4
	v_add_u32_e32 v17, v17, v5
	v_add_u32_e32 v17, v17, v6
	v_add_u32_e32 v17, v17, v7
	v_add_u32_e32 v17, v17, v8
	v_add_u32_e32 v17, v17, v9
	v_add_u32_e32 v17, v17, v10
	v_add_u32_e32 v17, v17, v11
	v_add_u32_e32 v17, v17, v12
	v_add_u32_e32 v17, v17, v13
	v_add_u32_e32 v17, v17, v14
	v_add_u32_e32 v17, v17, v15
	v_add_u32_e32 v17, v17, v16
	v_cmp_eq_u32_e32 vcc, s20, v17
	s_mov_b64 s[20:21], -1
	s_cbranch_vccnz .LBB0_509
	s_and_b32 s2, s29, 0xff
	s_cmp_eq_u32 s2, 0
	s_mov_b64 s[2:3], -1
	s_mov_b64 s[22:23], -1
	s_sleep 1
	s_cbranch_scc1 .LBB0_514
	s_and_b64 vcc, exec, s[22:23]
	s_cbranch_vccz .LBB0_509
